# gemm_out h=0 sub-steps: fragment reads ordered by first use (B[0], A0[0] first) with one counted lgkmcnt per MFMA of the first group; on top of the same change in gemm_in
# baseline (speedup 1.0000x reference)
.Lgout_loop:
	s_waitcnt vmcnt(8)
	s_barrier
	ds_read_b128 v[132:135], v196 offset:0
	ds_read_b128 v[90:93], v194 offset:0
	ds_read_b128 v[94:97], v194 offset:2048
	ds_read_b128 v[98:101], v194 offset:4096
	ds_read_b128 v[102:105], v194 offset:6144
	ds_read_b128 v[136:139], v196 offset:2048
	ds_read_b128 v[106:109], v195 offset:0
	ds_read_b128 v[110:113], v195 offset:2048
	ds_read_b128 v[114:117], v195 offset:4096
	ds_read_b128 v[118:121], v195 offset:6144
	ds_read_b128 v[140:143], v197 offset:0
	ds_read_b128 v[144:147], v197 offset:2048
	s_waitcnt lgkmcnt(10)
	s_add_u32 m0, s12, 0x10000
	v_mfma_f32_16x16x32_f16 v[124:127], v[90:93], v[132:135], v[124:127]
	global_load_lds_dwordx4 v190, s[10:11]
	s_waitcnt lgkmcnt(9)
	v_mfma_f32_16x16x32_f16 v[44:47], v[94:97], v[132:135], v[44:47]
	s_waitcnt lgkmcnt(8)
	v_mfma_f32_16x16x32_f16 v[28:31], v[98:101], v[132:135], v[28:31]
	s_waitcnt lgkmcnt(7)
	v_mfma_f32_16x16x32_f16 v[12:15], v[102:105], v[132:135], v[12:15]
	s_waitcnt lgkmcnt(6)
	s_add_u32 m0, s12, 0x11000
	v_mfma_f32_16x16x32_f16 v[56:59], v[90:93], v[136:139], v[56:59]
	global_load_lds_dwordx4 v192, s[10:11]
	v_mfma_f32_16x16x32_f16 v[40:43], v[94:97], v[136:139], v[40:43]
	v_mfma_f32_16x16x32_f16 v[24:27], v[98:101], v[136:139], v[24:27]
	v_mfma_f32_16x16x32_f16 v[8:11], v[102:105], v[136:139], v[8:11]
	s_waitcnt lgkmcnt(1)
	v_mfma_f32_16x16x32_f16 v[124:127], v[106:109], v[140:143], v[124:127]
	v_mfma_f32_16x16x32_f16 v[44:47], v[110:113], v[140:143], v[44:47]
	v_mfma_f32_16x16x32_f16 v[28:31], v[114:117], v[140:143], v[28:31]
	v_mfma_f32_16x16x32_f16 v[12:15], v[118:121], v[140:143], v[12:15]
	s_waitcnt lgkmcnt(0)
	v_mfma_f32_16x16x32_f16 v[56:59], v[106:109], v[144:147], v[56:59]
	v_mfma_f32_16x16x32_f16 v[40:43], v[110:113], v[144:147], v[40:43]
	v_mfma_f32_16x16x32_f16 v[24:27], v[114:117], v[144:147], v[24:27]
	v_mfma_f32_16x16x32_f16 v[8:11], v[118:121], v[144:147], v[8:11]
	s_add_u32 s10, s10, 128
	s_addc_u32 s11, s11, 0
	s_barrier
	ds_read_b128 v[174:177], v196 offset:8192
	ds_read_b128 v[178:181], v196 offset:10240
	ds_read_b128 v[182:185], v197 offset:8192
	ds_read_b128 v[186:189], v197 offset:10240
	s_waitcnt lgkmcnt(3)
	s_add_u32 m0, s12, 0x8000
	v_mfma_f32_16x16x32_f16 v[52:55], v[90:93], v[174:177], v[52:55]
	global_load_lds_dwordx4 v190, s[14:15]
	v_mfma_f32_16x16x32_f16 v[36:39], v[94:97], v[174:177], v[36:39]
	s_add_u32 m0, s12, 0x9000
	v_mfma_f32_16x16x32_f16 v[20:23], v[98:101], v[174:177], v[20:23]
	global_load_lds_dwordx4 v192, s[14:15]
	v_mfma_f32_16x16x32_f16 v[4:7], v[102:105], v[174:177], v[4:7]
	s_waitcnt lgkmcnt(2)
	s_add_u32 m0, s12, 0x0
	v_mfma_f32_16x16x32_f16 v[48:51], v[90:93], v[178:181], v[48:51]
	global_load_lds_dwordx4 v190, s[8:9]
	v_mfma_f32_16x16x32_f16 v[32:35], v[94:97], v[178:181], v[32:35]
	s_add_u32 m0, s12, 0x1000
	v_mfma_f32_16x16x32_f16 v[16:19], v[98:101], v[178:181], v[16:19]
	global_load_lds_dwordx4 v191, s[8:9]
	v_mfma_f32_16x16x32_f16 v[0:3], v[102:105], v[178:181], v[0:3]
	s_waitcnt lgkmcnt(1)
	s_add_u32 m0, s12, 0x2000
	v_mfma_f32_16x16x32_f16 v[52:55], v[106:109], v[182:185], v[52:55]
	global_load_lds_dwordx4 v192, s[8:9]
	v_mfma_f32_16x16x32_f16 v[36:39], v[110:113], v[182:185], v[36:39]
	v_mfma_f32_16x16x32_f16 v[20:23], v[114:117], v[182:185], v[20:23]
	v_mfma_f32_16x16x32_f16 v[4:7], v[118:121], v[182:185], v[4:7]
	s_waitcnt lgkmcnt(0)
	s_add_u32 m0, s12, 0x3000
	v_mfma_f32_16x16x32_f16 v[48:51], v[106:109], v[186:189], v[48:51]
	global_load_lds_dwordx4 v193, s[8:9]
	v_mfma_f32_16x16x32_f16 v[32:35], v[110:113], v[186:189], v[32:35]
	v_mfma_f32_16x16x32_f16 v[16:19], v[114:117], v[186:189], v[16:19]
	v_mfma_f32_16x16x32_f16 v[0:3], v[118:121], v[186:189], v[0:3]
	s_add_u32 s14, s14, 128
	s_addc_u32 s15, s15, 0
	s_add_u32 s8, s8, 128
	s_addc_u32 s9, s9, 0
	s_waitcnt vmcnt(8)
	s_barrier
	ds_read_b128 v[132:135], v196 offset:16384
	ds_read_b128 v[90:93], v194 offset:16384
	ds_read_b128 v[94:97], v194 offset:18432
	ds_read_b128 v[98:101], v194 offset:20480
	ds_read_b128 v[102:105], v194 offset:22528
	ds_read_b128 v[136:139], v196 offset:18432
	ds_read_b128 v[106:109], v195 offset:16384
	ds_read_b128 v[110:113], v195 offset:18432
	ds_read_b128 v[114:117], v195 offset:20480
	ds_read_b128 v[118:121], v195 offset:22528
	ds_read_b128 v[140:143], v197 offset:16384
	ds_read_b128 v[144:147], v197 offset:18432
	s_waitcnt lgkmcnt(10)
	s_add_u32 m0, s12, 0xa000
	v_mfma_f32_16x16x32_f16 v[124:127], v[90:93], v[132:135], v[124:127]
	global_load_lds_dwordx4 v190, s[10:11]
	s_waitcnt lgkmcnt(9)
	v_mfma_f32_16x16x32_f16 v[44:47], v[94:97], v[132:135], v[44:47]
	s_waitcnt lgkmcnt(8)
	v_mfma_f32_16x16x32_f16 v[28:31], v[98:101], v[132:135], v[28:31]
	s_waitcnt lgkmcnt(7)
	v_mfma_f32_16x16x32_f16 v[12:15], v[102:105], v[132:135], v[12:15]
	s_waitcnt lgkmcnt(6)
	s_add_u32 m0, s12, 0xb000
	v_mfma_f32_16x16x32_f16 v[56:59], v[90:93], v[136:139], v[56:59]
	global_load_lds_dwordx4 v192, s[10:11]
	v_mfma_f32_16x16x32_f16 v[40:43], v[94:97], v[136:139], v[40:43]
	v_mfma_f32_16x16x32_f16 v[24:27], v[98:101], v[136:139], v[24:27]
	v_mfma_f32_16x16x32_f16 v[8:11], v[102:105], v[136:139], v[8:11]
	s_waitcnt lgkmcnt(1)
	v_mfma_f32_16x16x32_f16 v[124:127], v[106:109], v[140:143], v[124:127]
	v_mfma_f32_16x16x32_f16 v[44:47], v[110:113], v[140:143], v[44:47]
	v_mfma_f32_16x16x32_f16 v[28:31], v[114:117], v[140:143], v[28:31]
	v_mfma_f32_16x16x32_f16 v[12:15], v[118:121], v[140:143], v[12:15]
	s_waitcnt lgkmcnt(0)
	v_mfma_f32_16x16x32_f16 v[56:59], v[106:109], v[144:147], v[56:59]
	v_mfma_f32_16x16x32_f16 v[40:43], v[110:113], v[144:147], v[40:43]
	v_mfma_f32_16x16x32_f16 v[24:27], v[114:117], v[144:147], v[24:27]
	v_mfma_f32_16x16x32_f16 v[8:11], v[118:121], v[144:147], v[8:11]
	s_add_u32 s10, s10, 128
	s_addc_u32 s11, s11, 0
	s_barrier
	ds_read_b128 v[174:177], v196 offset:24576
	ds_read_b128 v[178:181], v196 offset:26624
	ds_read_b128 v[182:185], v197 offset:24576
	ds_read_b128 v[186:189], v197 offset:26624
	s_waitcnt lgkmcnt(3)
	s_add_u32 m0, s12, 0xc000
	v_mfma_f32_16x16x32_f16 v[52:55], v[90:93], v[174:177], v[52:55]
	global_load_lds_dwordx4 v190, s[14:15]
	v_mfma_f32_16x16x32_f16 v[36:39], v[94:97], v[174:177], v[36:39]
	s_add_u32 m0, s12, 0xd000
	v_mfma_f32_16x16x32_f16 v[20:23], v[98:101], v[174:177], v[20:23]
	global_load_lds_dwordx4 v192, s[14:15]
	v_mfma_f32_16x16x32_f16 v[4:7], v[102:105], v[174:177], v[4:7]
	s_waitcnt lgkmcnt(2)
	s_add_u32 m0, s12, 0x4000
	v_mfma_f32_16x16x32_f16 v[48:51], v[90:93], v[178:181], v[48:51]
	global_load_lds_dwordx4 v190, s[8:9]
	v_mfma_f32_16x16x32_f16 v[32:35], v[94:97], v[178:181], v[32:35]
	s_add_u32 m0, s12, 0x5000
	v_mfma_f32_16x16x32_f16 v[16:19], v[98:101], v[178:181], v[16:19]
	global_load_lds_dwordx4 v191, s[8:9]
	v_mfma_f32_16x16x32_f16 v[0:3], v[102:105], v[178:181], v[0:3]
	s_waitcnt lgkmcnt(1)
	s_add_u32 m0, s12, 0x6000
	v_mfma_f32_16x16x32_f16 v[52:55], v[106:109], v[182:185], v[52:55]
	global_load_lds_dwordx4 v192, s[8:9]
	v_mfma_f32_16x16x32_f16 v[36:39], v[110:113], v[182:185], v[36:39]
	v_mfma_f32_16x16x32_f16 v[20:23], v[114:117], v[182:185], v[20:23]
	v_mfma_f32_16x16x32_f16 v[4:7], v[118:121], v[182:185], v[4:7]
	s_waitcnt lgkmcnt(0)
	s_add_u32 m0, s12, 0x7000
	v_mfma_f32_16x16x32_f16 v[48:51], v[106:109], v[186:189], v[48:51]
	global_load_lds_dwordx4 v193, s[8:9]
	v_mfma_f32_16x16x32_f16 v[32:35], v[110:113], v[186:189], v[32:35]
	v_mfma_f32_16x16x32_f16 v[16:19], v[114:117], v[186:189], v[16:19]
	v_mfma_f32_16x16x32_f16 v[0:3], v[118:121], v[186:189], v[0:3]
	s_add_u32 s14, s14, 128
	s_addc_u32 s15, s15, 0
	s_add_u32 s8, s8, 128
	s_addc_u32 s9, s9, 0
	s_waitcnt vmcnt(8)
	s_barrier
	ds_read_b128 v[132:135], v196 offset:32768
	ds_read_b128 v[90:93], v194 offset:0
	ds_read_b128 v[94:97], v194 offset:2048
	ds_read_b128 v[98:101], v194 offset:4096
	ds_read_b128 v[102:105], v194 offset:6144
	ds_read_b128 v[136:139], v196 offset:34816
	ds_read_b128 v[106:109], v195 offset:0
	ds_read_b128 v[110:113], v195 offset:2048
	ds_read_b128 v[114:117], v195 offset:4096
	ds_read_b128 v[118:121], v195 offset:6144
	ds_read_b128 v[140:143], v197 offset:32768
	ds_read_b128 v[144:147], v197 offset:34816
	s_waitcnt lgkmcnt(10)
	s_add_u32 m0, s12, 0xe000
	v_mfma_f32_16x16x32_f16 v[124:127], v[90:93], v[132:135], v[124:127]
	global_load_lds_dwordx4 v190, s[10:11]
	s_waitcnt lgkmcnt(9)
	v_mfma_f32_16x16x32_f16 v[44:47], v[94:97], v[132:135], v[44:47]
	s_waitcnt lgkmcnt(8)
	v_mfma_f32_16x16x32_f16 v[28:31], v[98:101], v[132:135], v[28:31]
	s_waitcnt lgkmcnt(7)
	v_mfma_f32_16x16x32_f16 v[12:15], v[102:105], v[132:135], v[12:15]
	s_waitcnt lgkmcnt(6)
	s_add_u32 m0, s12, 0xf000
	v_mfma_f32_16x16x32_f16 v[56:59], v[90:93], v[136:139], v[56:59]
	global_load_lds_dwordx4 v192, s[10:11]
	v_mfma_f32_16x16x32_f16 v[40:43], v[94:97], v[136:139], v[40:43]
	v_mfma_f32_16x16x32_f16 v[24:27], v[98:101], v[136:139], v[24:27]
	v_mfma_f32_16x16x32_f16 v[8:11], v[102:105], v[136:139], v[8:11]
	s_waitcnt lgkmcnt(1)
	v_mfma_f32_16x16x32_f16 v[124:127], v[106:109], v[140:143], v[124:127]
	v_mfma_f32_16x16x32_f16 v[44:47], v[110:113], v[140:143], v[44:47]
	v_mfma_f32_16x16x32_f16 v[28:31], v[114:117], v[140:143], v[28:31]
	v_mfma_f32_16x16x32_f16 v[12:15], v[118:121], v[140:143], v[12:15]
	s_waitcnt lgkmcnt(0)
	v_mfma_f32_16x16x32_f16 v[56:59], v[106:109], v[144:147], v[56:59]
	v_mfma_f32_16x16x32_f16 v[40:43], v[110:113], v[144:147], v[40:43]
	v_mfma_f32_16x16x32_f16 v[24:27], v[114:117], v[144:147], v[24:27]
	v_mfma_f32_16x16x32_f16 v[8:11], v[118:121], v[144:147], v[8:11]
	s_add_u32 s10, s10, 128
	s_addc_u32 s11, s11, 0
	s_barrier
	ds_read_b128 v[174:177], v196 offset:0
	ds_read_b128 v[178:181], v196 offset:2048
	ds_read_b128 v[182:185], v197 offset:0
	ds_read_b128 v[186:189], v197 offset:2048
	s_waitcnt lgkmcnt(3)
	s_add_u32 m0, s12, 0x10000
	v_mfma_f32_16x16x32_f16 v[52:55], v[90:93], v[174:177], v[52:55]
	global_load_lds_dwordx4 v190, s[14:15]
	v_mfma_f32_16x16x32_f16 v[36:39], v[94:97], v[174:177], v[36:39]
	s_add_u32 m0, s12, 0x11000
	v_mfma_f32_16x16x32_f16 v[20:23], v[98:101], v[174:177], v[20:23]
	global_load_lds_dwordx4 v192, s[14:15]
	v_mfma_f32_16x16x32_f16 v[4:7], v[102:105], v[174:177], v[4:7]
	s_waitcnt lgkmcnt(2)
	s_add_u32 m0, s12, 0x0
	v_mfma_f32_16x16x32_f16 v[48:51], v[90:93], v[178:181], v[48:51]
	global_load_lds_dwordx4 v190, s[8:9]
	v_mfma_f32_16x16x32_f16 v[32:35], v[94:97], v[178:181], v[32:35]
	s_add_u32 m0, s12, 0x1000
	v_mfma_f32_16x16x32_f16 v[16:19], v[98:101], v[178:181], v[16:19]
	global_load_lds_dwordx4 v191, s[8:9]
	v_mfma_f32_16x16x32_f16 v[0:3], v[102:105], v[178:181], v[0:3]
	s_waitcnt lgkmcnt(1)
	s_add_u32 m0, s12, 0x2000
	v_mfma_f32_16x16x32_f16 v[52:55], v[106:109], v[182:185], v[52:55]
	global_load_lds_dwordx4 v192, s[8:9]
	v_mfma_f32_16x16x32_f16 v[36:39], v[110:113], v[182:185], v[36:39]
	v_mfma_f32_16x16x32_f16 v[20:23], v[114:117], v[182:185], v[20:23]
	v_mfma_f32_16x16x32_f16 v[4:7], v[118:121], v[182:185], v[4:7]
	s_waitcnt lgkmcnt(0)
	s_add_u32 m0, s12, 0x3000
	v_mfma_f32_16x16x32_f16 v[48:51], v[106:109], v[186:189], v[48:51]
	global_load_lds_dwordx4 v193, s[8:9]
	v_mfma_f32_16x16x32_f16 v[32:35], v[110:113], v[186:189], v[32:35]
	v_mfma_f32_16x16x32_f16 v[16:19], v[114:117], v[186:189], v[16:19]
	v_mfma_f32_16x16x32_f16 v[0:3], v[118:121], v[186:189], v[0:3]
	s_add_u32 s14, s14, 128
	s_addc_u32 s15, s15, 0
	s_add_u32 s8, s8, 128
	s_addc_u32 s9, s9, 0
	s_waitcnt vmcnt(8)
	s_barrier
	ds_read_b128 v[132:135], v196 offset:8192
	ds_read_b128 v[90:93], v194 offset:16384
	ds_read_b128 v[94:97], v194 offset:18432
	ds_read_b128 v[98:101], v194 offset:20480
	ds_read_b128 v[102:105], v194 offset:22528
	ds_read_b128 v[136:139], v196 offset:10240
	ds_read_b128 v[106:109], v195 offset:16384
	ds_read_b128 v[110:113], v195 offset:18432
	ds_read_b128 v[114:117], v195 offset:20480
	ds_read_b128 v[118:121], v195 offset:22528
	ds_read_b128 v[140:143], v197 offset:8192
	ds_read_b128 v[144:147], v197 offset:10240
	s_waitcnt lgkmcnt(10)
	s_add_u32 m0, s12, 0x8000
	v_mfma_f32_16x16x32_f16 v[124:127], v[90:93], v[132:135], v[124:127]
	global_load_lds_dwordx4 v190, s[10:11]
	s_waitcnt lgkmcnt(9)
	v_mfma_f32_16x16x32_f16 v[44:47], v[94:97], v[132:135], v[44:47]
	s_waitcnt lgkmcnt(8)
	v_mfma_f32_16x16x32_f16 v[28:31], v[98:101], v[132:135], v[28:31]
	s_waitcnt lgkmcnt(7)
	v_mfma_f32_16x16x32_f16 v[12:15], v[102:105], v[132:135], v[12:15]
	s_waitcnt lgkmcnt(6)
	s_add_u32 m0, s12, 0x9000
	v_mfma_f32_16x16x32_f16 v[56:59], v[90:93], v[136:139], v[56:59]
	global_load_lds_dwordx4 v192, s[10:11]
	v_mfma_f32_16x16x32_f16 v[40:43], v[94:97], v[136:139], v[40:43]
	v_mfma_f32_16x16x32_f16 v[24:27], v[98:101], v[136:139], v[24:27]
	v_mfma_f32_16x16x32_f16 v[8:11], v[102:105], v[136:139], v[8:11]
	s_waitcnt lgkmcnt(1)
	v_mfma_f32_16x16x32_f16 v[124:127], v[106:109], v[140:143], v[124:127]
	v_mfma_f32_16x16x32_f16 v[44:47], v[110:113], v[140:143], v[44:47]
	v_mfma_f32_16x16x32_f16 v[28:31], v[114:117], v[140:143], v[28:31]
	v_mfma_f32_16x16x32_f16 v[12:15], v[118:121], v[140:143], v[12:15]
	s_waitcnt lgkmcnt(0)
	v_mfma_f32_16x16x32_f16 v[56:59], v[106:109], v[144:147], v[56:59]
	v_mfma_f32_16x16x32_f16 v[40:43], v[110:113], v[144:147], v[40:43]
	v_mfma_f32_16x16x32_f16 v[24:27], v[114:117], v[144:147], v[24:27]
	v_mfma_f32_16x16x32_f16 v[8:11], v[118:121], v[144:147], v[8:11]
	s_add_u32 s10, s10, 128
	s_addc_u32 s11, s11, 0
	s_barrier
	ds_read_b128 v[174:177], v196 offset:16384
	ds_read_b128 v[178:181], v196 offset:18432
	ds_read_b128 v[182:185], v197 offset:16384
	ds_read_b128 v[186:189], v197 offset:18432
	s_waitcnt lgkmcnt(3)
	s_add_u32 m0, s12, 0xa000
	v_mfma_f32_16x16x32_f16 v[52:55], v[90:93], v[174:177], v[52:55]
	global_load_lds_dwordx4 v190, s[14:15]
	v_mfma_f32_16x16x32_f16 v[36:39], v[94:97], v[174:177], v[36:39]
	s_add_u32 m0, s12, 0xb000
	v_mfma_f32_16x16x32_f16 v[20:23], v[98:101], v[174:177], v[20:23]
	global_load_lds_dwordx4 v192, s[14:15]
	v_mfma_f32_16x16x32_f16 v[4:7], v[102:105], v[174:177], v[4:7]
	s_waitcnt lgkmcnt(2)
	s_add_u32 m0, s12, 0x4000
	v_mfma_f32_16x16x32_f16 v[48:51], v[90:93], v[178:181], v[48:51]
	global_load_lds_dwordx4 v190, s[8:9]
	v_mfma_f32_16x16x32_f16 v[32:35], v[94:97], v[178:181], v[32:35]
	s_add_u32 m0, s12, 0x5000
	v_mfma_f32_16x16x32_f16 v[16:19], v[98:101], v[178:181], v[16:19]
	global_load_lds_dwordx4 v191, s[8:9]
	v_mfma_f32_16x16x32_f16 v[0:3], v[102:105], v[178:181], v[0:3]
	s_waitcnt lgkmcnt(1)
	s_add_u32 m0, s12, 0x6000
	v_mfma_f32_16x16x32_f16 v[52:55], v[106:109], v[182:185], v[52:55]
	global_load_lds_dwordx4 v192, s[8:9]
	v_mfma_f32_16x16x32_f16 v[36:39], v[110:113], v[182:185], v[36:39]
	v_mfma_f32_16x16x32_f16 v[20:23], v[114:117], v[182:185], v[20:23]
	v_mfma_f32_16x16x32_f16 v[4:7], v[118:121], v[182:185], v[4:7]
	s_waitcnt lgkmcnt(0)
	s_add_u32 m0, s12, 0x7000
	v_mfma_f32_16x16x32_f16 v[48:51], v[106:109], v[186:189], v[48:51]
	global_load_lds_dwordx4 v193, s[8:9]
	v_mfma_f32_16x16x32_f16 v[32:35], v[110:113], v[186:189], v[32:35]
	v_mfma_f32_16x16x32_f16 v[16:19], v[114:117], v[186:189], v[16:19]
	v_mfma_f32_16x16x32_f16 v[0:3], v[118:121], v[186:189], v[0:3]
	s_add_u32 s14, s14, 128
	s_addc_u32 s15, s15, 0
	s_add_u32 s8, s8, 128
	s_addc_u32 s9, s9, 0
	s_waitcnt vmcnt(8)
	s_barrier
	ds_read_b128 v[132:135], v196 offset:24576
	ds_read_b128 v[90:93], v194 offset:0
	ds_read_b128 v[94:97], v194 offset:2048
	ds_read_b128 v[98:101], v194 offset:4096
	ds_read_b128 v[102:105], v194 offset:6144
	ds_read_b128 v[136:139], v196 offset:26624
	ds_read_b128 v[106:109], v195 offset:0
	ds_read_b128 v[110:113], v195 offset:2048
	ds_read_b128 v[114:117], v195 offset:4096
	ds_read_b128 v[118:121], v195 offset:6144
	ds_read_b128 v[140:143], v197 offset:24576
	ds_read_b128 v[144:147], v197 offset:26624
	s_waitcnt lgkmcnt(10)
	s_add_u32 m0, s12, 0xc000
	v_mfma_f32_16x16x32_f16 v[124:127], v[90:93], v[132:135], v[124:127]
	global_load_lds_dwordx4 v190, s[10:11]
	s_waitcnt lgkmcnt(9)
	v_mfma_f32_16x16x32_f16 v[44:47], v[94:97], v[132:135], v[44:47]
	s_waitcnt lgkmcnt(8)
	v_mfma_f32_16x16x32_f16 v[28:31], v[98:101], v[132:135], v[28:31]
	s_waitcnt lgkmcnt(7)
	v_mfma_f32_16x16x32_f16 v[12:15], v[102:105], v[132:135], v[12:15]
	s_waitcnt lgkmcnt(6)
	s_add_u32 m0, s12, 0xd000
	v_mfma_f32_16x16x32_f16 v[56:59], v[90:93], v[136:139], v[56:59]
	global_load_lds_dwordx4 v192, s[10:11]
	v_mfma_f32_16x16x32_f16 v[40:43], v[94:97], v[136:139], v[40:43]
	v_mfma_f32_16x16x32_f16 v[24:27], v[98:101], v[136:139], v[24:27]
	v_mfma_f32_16x16x32_f16 v[8:11], v[102:105], v[136:139], v[8:11]
	s_waitcnt lgkmcnt(1)
	v_mfma_f32_16x16x32_f16 v[124:127], v[106:109], v[140:143], v[124:127]
	v_mfma_f32_16x16x32_f16 v[44:47], v[110:113], v[140:143], v[44:47]
	v_mfma_f32_16x16x32_f16 v[28:31], v[114:117], v[140:143], v[28:31]
	v_mfma_f32_16x16x32_f16 v[12:15], v[118:121], v[140:143], v[12:15]
	s_waitcnt lgkmcnt(0)
	v_mfma_f32_16x16x32_f16 v[56:59], v[106:109], v[144:147], v[56:59]
	v_mfma_f32_16x16x32_f16 v[40:43], v[110:113], v[144:147], v[40:43]
	v_mfma_f32_16x16x32_f16 v[24:27], v[114:117], v[144:147], v[24:27]
	v_mfma_f32_16x16x32_f16 v[8:11], v[118:121], v[144:147], v[8:11]
	s_add_u32 s10, s10, 128
	s_addc_u32 s11, s11, 0
	s_barrier
	ds_read_b128 v[174:177], v196 offset:32768
	ds_read_b128 v[178:181], v196 offset:34816
	ds_read_b128 v[182:185], v197 offset:32768
	ds_read_b128 v[186:189], v197 offset:34816
	s_waitcnt lgkmcnt(3)
	s_add_u32 m0, s12, 0xe000
	v_mfma_f32_16x16x32_f16 v[52:55], v[90:93], v[174:177], v[52:55]
	global_load_lds_dwordx4 v190, s[14:15]
	v_mfma_f32_16x16x32_f16 v[36:39], v[94:97], v[174:177], v[36:39]
	s_add_u32 m0, s12, 0xf000
	v_mfma_f32_16x16x32_f16 v[20:23], v[98:101], v[174:177], v[20:23]
	global_load_lds_dwordx4 v192, s[14:15]
	v_mfma_f32_16x16x32_f16 v[4:7], v[102:105], v[174:177], v[4:7]
	s_waitcnt lgkmcnt(2)
	s_add_u32 m0, s12, 0x0
	v_mfma_f32_16x16x32_f16 v[48:51], v[90:93], v[178:181], v[48:51]
	global_load_lds_dwordx4 v190, s[8:9]
	v_mfma_f32_16x16x32_f16 v[32:35], v[94:97], v[178:181], v[32:35]
	s_add_u32 m0, s12, 0x1000
	v_mfma_f32_16x16x32_f16 v[16:19], v[98:101], v[178:181], v[16:19]
	global_load_lds_dwordx4 v191, s[8:9]
	v_mfma_f32_16x16x32_f16 v[0:3], v[102:105], v[178:181], v[0:3]
	s_waitcnt lgkmcnt(1)
	s_add_u32 m0, s12, 0x2000
	v_mfma_f32_16x16x32_f16 v[52:55], v[106:109], v[182:185], v[52:55]
	global_load_lds_dwordx4 v192, s[8:9]
	v_mfma_f32_16x16x32_f16 v[36:39], v[110:113], v[182:185], v[36:39]
	v_mfma_f32_16x16x32_f16 v[20:23], v[114:117], v[182:185], v[20:23]
	v_mfma_f32_16x16x32_f16 v[4:7], v[118:121], v[182:185], v[4:7]
	s_waitcnt lgkmcnt(0)
	s_add_u32 m0, s12, 0x3000
	v_mfma_f32_16x16x32_f16 v[48:51], v[106:109], v[186:189], v[48:51]
	global_load_lds_dwordx4 v193, s[8:9]
	v_mfma_f32_16x16x32_f16 v[32:35], v[110:113], v[186:189], v[32:35]
	v_mfma_f32_16x16x32_f16 v[16:19], v[114:117], v[186:189], v[16:19]
	v_mfma_f32_16x16x32_f16 v[0:3], v[118:121], v[186:189], v[0:3]
	s_add_u32 s14, s14, 128
	s_addc_u32 s15, s15, 0
	s_add_u32 s8, s8, 128
	s_addc_u32 s9, s9, 0
	s_waitcnt vmcnt(8)
	s_barrier
	ds_read_b128 v[132:135], v196 offset:0
	ds_read_b128 v[90:93], v194 offset:16384
	ds_read_b128 v[94:97], v194 offset:18432
	ds_read_b128 v[98:101], v194 offset:20480
	ds_read_b128 v[102:105], v194 offset:22528
	ds_read_b128 v[136:139], v196 offset:2048
	ds_read_b128 v[106:109], v195 offset:16384
	ds_read_b128 v[110:113], v195 offset:18432
	ds_read_b128 v[114:117], v195 offset:20480
	ds_read_b128 v[118:121], v195 offset:22528
	ds_read_b128 v[140:143], v197 offset:0
	ds_read_b128 v[144:147], v197 offset:2048
	s_waitcnt lgkmcnt(10)
	s_add_u32 m0, s12, 0x10000
	v_mfma_f32_16x16x32_f16 v[124:127], v[90:93], v[132:135], v[124:127]
	global_load_lds_dwordx4 v190, s[10:11]
	s_waitcnt lgkmcnt(9)
	v_mfma_f32_16x16x32_f16 v[44:47], v[94:97], v[132:135], v[44:47]
	s_waitcnt lgkmcnt(8)
	v_mfma_f32_16x16x32_f16 v[28:31], v[98:101], v[132:135], v[28:31]
	s_waitcnt lgkmcnt(7)
	v_mfma_f32_16x16x32_f16 v[12:15], v[102:105], v[132:135], v[12:15]
	s_waitcnt lgkmcnt(6)
	s_add_u32 m0, s12, 0x11000
	v_mfma_f32_16x16x32_f16 v[56:59], v[90:93], v[136:139], v[56:59]
	global_load_lds_dwordx4 v192, s[10:11]
	v_mfma_f32_16x16x32_f16 v[40:43], v[94:97], v[136:139], v[40:43]
	v_mfma_f32_16x16x32_f16 v[24:27], v[98:101], v[136:139], v[24:27]
	v_mfma_f32_16x16x32_f16 v[8:11], v[102:105], v[136:139], v[8:11]
	s_waitcnt lgkmcnt(1)
	v_mfma_f32_16x16x32_f16 v[124:127], v[106:109], v[140:143], v[124:127]
	v_mfma_f32_16x16x32_f16 v[44:47], v[110:113], v[140:143], v[44:47]
	v_mfma_f32_16x16x32_f16 v[28:31], v[114:117], v[140:143], v[28:31]
	v_mfma_f32_16x16x32_f16 v[12:15], v[118:121], v[140:143], v[12:15]
	s_waitcnt lgkmcnt(0)
	v_mfma_f32_16x16x32_f16 v[56:59], v[106:109], v[144:147], v[56:59]
	v_mfma_f32_16x16x32_f16 v[40:43], v[110:113], v[144:147], v[40:43]
	v_mfma_f32_16x16x32_f16 v[24:27], v[114:117], v[144:147], v[24:27]
	v_mfma_f32_16x16x32_f16 v[8:11], v[118:121], v[144:147], v[8:11]
	s_add_u32 s10, s10, 128
	s_addc_u32 s11, s11, 0
	s_barrier
	ds_read_b128 v[174:177], v196 offset:8192
	ds_read_b128 v[178:181], v196 offset:10240
	ds_read_b128 v[182:185], v197 offset:8192
	ds_read_b128 v[186:189], v197 offset:10240
	s_waitcnt lgkmcnt(3)
	s_add_u32 m0, s12, 0x8000
	v_mfma_f32_16x16x32_f16 v[52:55], v[90:93], v[174:177], v[52:55]
	global_load_lds_dwordx4 v190, s[14:15]
	v_mfma_f32_16x16x32_f16 v[36:39], v[94:97], v[174:177], v[36:39]
	s_add_u32 m0, s12, 0x9000
	v_mfma_f32_16x16x32_f16 v[20:23], v[98:101], v[174:177], v[20:23]
	global_load_lds_dwordx4 v192, s[14:15]
	v_mfma_f32_16x16x32_f16 v[4:7], v[102:105], v[174:177], v[4:7]
	s_waitcnt lgkmcnt(2)
	s_add_u32 m0, s12, 0x4000
	v_mfma_f32_16x16x32_f16 v[48:51], v[90:93], v[178:181], v[48:51]
	global_load_lds_dwordx4 v190, s[8:9]
	v_mfma_f32_16x16x32_f16 v[32:35], v[94:97], v[178:181], v[32:35]
	s_add_u32 m0, s12, 0x5000
	v_mfma_f32_16x16x32_f16 v[16:19], v[98:101], v[178:181], v[16:19]
	global_load_lds_dwordx4 v191, s[8:9]
	v_mfma_f32_16x16x32_f16 v[0:3], v[102:105], v[178:181], v[0:3]
	s_waitcnt lgkmcnt(1)
	s_add_u32 m0, s12, 0x6000
	v_mfma_f32_16x16x32_f16 v[52:55], v[106:109], v[182:185], v[52:55]
	global_load_lds_dwordx4 v192, s[8:9]
	v_mfma_f32_16x16x32_f16 v[36:39], v[110:113], v[182:185], v[36:39]
	v_mfma_f32_16x16x32_f16 v[20:23], v[114:117], v[182:185], v[20:23]
	v_mfma_f32_16x16x32_f16 v[4:7], v[118:121], v[182:185], v[4:7]
	s_waitcnt lgkmcnt(0)
	s_add_u32 m0, s12, 0x7000
	v_mfma_f32_16x16x32_f16 v[48:51], v[106:109], v[186:189], v[48:51]
	global_load_lds_dwordx4 v193, s[8:9]
	v_mfma_f32_16x16x32_f16 v[32:35], v[110:113], v[186:189], v[32:35]
	v_mfma_f32_16x16x32_f16 v[16:19], v[114:117], v[186:189], v[16:19]
	v_mfma_f32_16x16x32_f16 v[0:3], v[118:121], v[186:189], v[0:3]
	s_add_u32 s14, s14, 128
	s_addc_u32 s15, s15, 0
	s_add_u32 s8, s8, 128
	s_addc_u32 s9, s9, 0
	s_waitcnt vmcnt(8)
	s_barrier
	ds_read_b128 v[132:135], v196 offset:16384
	ds_read_b128 v[90:93], v194 offset:0
	ds_read_b128 v[94:97], v194 offset:2048
	ds_read_b128 v[98:101], v194 offset:4096
	ds_read_b128 v[102:105], v194 offset:6144
	ds_read_b128 v[136:139], v196 offset:18432
	ds_read_b128 v[106:109], v195 offset:0
	ds_read_b128 v[110:113], v195 offset:2048
	ds_read_b128 v[114:117], v195 offset:4096
	ds_read_b128 v[118:121], v195 offset:6144
	ds_read_b128 v[140:143], v197 offset:16384
	ds_read_b128 v[144:147], v197 offset:18432
	s_waitcnt lgkmcnt(10)
	s_add_u32 m0, s12, 0xa000
	v_mfma_f32_16x16x32_f16 v[124:127], v[90:93], v[132:135], v[124:127]
	global_load_lds_dwordx4 v190, s[10:11]
	s_waitcnt lgkmcnt(9)
	v_mfma_f32_16x16x32_f16 v[44:47], v[94:97], v[132:135], v[44:47]
	s_waitcnt lgkmcnt(8)
	v_mfma_f32_16x16x32_f16 v[28:31], v[98:101], v[132:135], v[28:31]
	s_waitcnt lgkmcnt(7)
	v_mfma_f32_16x16x32_f16 v[12:15], v[102:105], v[132:135], v[12:15]
	s_waitcnt lgkmcnt(6)
	s_add_u32 m0, s12, 0xb000
	v_mfma_f32_16x16x32_f16 v[56:59], v[90:93], v[136:139], v[56:59]
	global_load_lds_dwordx4 v192, s[10:11]
	v_mfma_f32_16x16x32_f16 v[40:43], v[94:97], v[136:139], v[40:43]
	v_mfma_f32_16x16x32_f16 v[24:27], v[98:101], v[136:139], v[24:27]
	v_mfma_f32_16x16x32_f16 v[8:11], v[102:105], v[136:139], v[8:11]
	s_waitcnt lgkmcnt(1)
	v_mfma_f32_16x16x32_f16 v[124:127], v[106:109], v[140:143], v[124:127]
	v_mfma_f32_16x16x32_f16 v[44:47], v[110:113], v[140:143], v[44:47]
	v_mfma_f32_16x16x32_f16 v[28:31], v[114:117], v[140:143], v[28:31]
	v_mfma_f32_16x16x32_f16 v[12:15], v[118:121], v[140:143], v[12:15]
	s_waitcnt lgkmcnt(0)
	v_mfma_f32_16x16x32_f16 v[56:59], v[106:109], v[144:147], v[56:59]
	v_mfma_f32_16x16x32_f16 v[40:43], v[110:113], v[144:147], v[40:43]
	v_mfma_f32_16x16x32_f16 v[24:27], v[114:117], v[144:147], v[24:27]
	v_mfma_f32_16x16x32_f16 v[8:11], v[118:121], v[144:147], v[8:11]
	s_add_u32 s10, s10, 128
	s_addc_u32 s11, s11, 0
	s_barrier
	ds_read_b128 v[174:177], v196 offset:24576
	ds_read_b128 v[178:181], v196 offset:26624
	ds_read_b128 v[182:185], v197 offset:24576
	ds_read_b128 v[186:189], v197 offset:26624
	s_waitcnt lgkmcnt(3)
	s_add_u32 m0, s12, 0xc000
	v_mfma_f32_16x16x32_f16 v[52:55], v[90:93], v[174:177], v[52:55]
	global_load_lds_dwordx4 v190, s[14:15]
	v_mfma_f32_16x16x32_f16 v[36:39], v[94:97], v[174:177], v[36:39]
	s_add_u32 m0, s12, 0xd000
	v_mfma_f32_16x16x32_f16 v[20:23], v[98:101], v[174:177], v[20:23]
	global_load_lds_dwordx4 v192, s[14:15]
	v_mfma_f32_16x16x32_f16 v[4:7], v[102:105], v[174:177], v[4:7]
	s_waitcnt lgkmcnt(2)
	s_add_u32 m0, s12, 0x0
	v_mfma_f32_16x16x32_f16 v[48:51], v[90:93], v[178:181], v[48:51]
	global_load_lds_dwordx4 v190, s[8:9]
	v_mfma_f32_16x16x32_f16 v[32:35], v[94:97], v[178:181], v[32:35]
	s_add_u32 m0, s12, 0x1000
	v_mfma_f32_16x16x32_f16 v[16:19], v[98:101], v[178:181], v[16:19]
	global_load_lds_dwordx4 v191, s[8:9]
	v_mfma_f32_16x16x32_f16 v[0:3], v[102:105], v[178:181], v[0:3]
	s_waitcnt lgkmcnt(1)
	s_add_u32 m0, s12, 0x2000
	v_mfma_f32_16x16x32_f16 v[52:55], v[106:109], v[182:185], v[52:55]
	global_load_lds_dwordx4 v192, s[8:9]
	v_mfma_f32_16x16x32_f16 v[36:39], v[110:113], v[182:185], v[36:39]
	v_mfma_f32_16x16x32_f16 v[20:23], v[114:117], v[182:185], v[20:23]
	v_mfma_f32_16x16x32_f16 v[4:7], v[118:121], v[182:185], v[4:7]
	s_waitcnt lgkmcnt(0)
	s_add_u32 m0, s12, 0x3000
	v_mfma_f32_16x16x32_f16 v[48:51], v[106:109], v[186:189], v[48:51]
	global_load_lds_dwordx4 v193, s[8:9]
	v_mfma_f32_16x16x32_f16 v[32:35], v[110:113], v[186:189], v[32:35]
	v_mfma_f32_16x16x32_f16 v[16:19], v[114:117], v[186:189], v[16:19]
	v_mfma_f32_16x16x32_f16 v[0:3], v[118:121], v[186:189], v[0:3]
	s_add_u32 s14, s14, 128
	s_addc_u32 s15, s15, 0
	s_add_u32 s8, s8, 128
	s_addc_u32 s9, s9, 0
	s_waitcnt vmcnt(8)
	s_barrier
	ds_read_b128 v[132:135], v196 offset:32768
	ds_read_b128 v[90:93], v194 offset:16384
	ds_read_b128 v[94:97], v194 offset:18432
	ds_read_b128 v[98:101], v194 offset:20480
	ds_read_b128 v[102:105], v194 offset:22528
	ds_read_b128 v[136:139], v196 offset:34816
	ds_read_b128 v[106:109], v195 offset:16384
	ds_read_b128 v[110:113], v195 offset:18432
	ds_read_b128 v[114:117], v195 offset:20480
	ds_read_b128 v[118:121], v195 offset:22528
	ds_read_b128 v[140:143], v197 offset:32768
	ds_read_b128 v[144:147], v197 offset:34816
	s_waitcnt lgkmcnt(10)
	s_add_u32 m0, s12, 0xe000
	v_mfma_f32_16x16x32_f16 v[124:127], v[90:93], v[132:135], v[124:127]
	global_load_lds_dwordx4 v190, s[10:11]
	s_waitcnt lgkmcnt(9)
	v_mfma_f32_16x16x32_f16 v[44:47], v[94:97], v[132:135], v[44:47]
	s_waitcnt lgkmcnt(8)
	v_mfma_f32_16x16x32_f16 v[28:31], v[98:101], v[132:135], v[28:31]
	s_waitcnt lgkmcnt(7)
	v_mfma_f32_16x16x32_f16 v[12:15], v[102:105], v[132:135], v[12:15]
	s_waitcnt lgkmcnt(6)
	s_add_u32 m0, s12, 0xf000
	v_mfma_f32_16x16x32_f16 v[56:59], v[90:93], v[136:139], v[56:59]
	global_load_lds_dwordx4 v192, s[10:11]
	v_mfma_f32_16x16x32_f16 v[40:43], v[94:97], v[136:139], v[40:43]
	v_mfma_f32_16x16x32_f16 v[24:27], v[98:101], v[136:139], v[24:27]
	v_mfma_f32_16x16x32_f16 v[8:11], v[102:105], v[136:139], v[8:11]
	s_waitcnt lgkmcnt(1)
	v_mfma_f32_16x16x32_f16 v[124:127], v[106:109], v[140:143], v[124:127]
	v_mfma_f32_16x16x32_f16 v[44:47], v[110:113], v[140:143], v[44:47]
	v_mfma_f32_16x16x32_f16 v[28:31], v[114:117], v[140:143], v[28:31]
	v_mfma_f32_16x16x32_f16 v[12:15], v[118:121], v[140:143], v[12:15]
	s_waitcnt lgkmcnt(0)
	v_mfma_f32_16x16x32_f16 v[56:59], v[106:109], v[144:147], v[56:59]
	v_mfma_f32_16x16x32_f16 v[40:43], v[110:113], v[144:147], v[40:43]
	v_mfma_f32_16x16x32_f16 v[24:27], v[114:117], v[144:147], v[24:27]
	v_mfma_f32_16x16x32_f16 v[8:11], v[118:121], v[144:147], v[8:11]
	s_add_u32 s10, s10, 128
	s_addc_u32 s11, s11, 0
	s_barrier
	ds_read_b128 v[174:177], v196 offset:0
	ds_read_b128 v[178:181], v196 offset:2048
	ds_read_b128 v[182:185], v197 offset:0
	ds_read_b128 v[186:189], v197 offset:2048
	s_waitcnt lgkmcnt(3)
	s_add_u32 m0, s12, 0x10000
	v_mfma_f32_16x16x32_f16 v[52:55], v[90:93], v[174:177], v[52:55]
	global_load_lds_dwordx4 v190, s[14:15]
	v_mfma_f32_16x16x32_f16 v[36:39], v[94:97], v[174:177], v[36:39]
	s_add_u32 m0, s12, 0x11000
	v_mfma_f32_16x16x32_f16 v[20:23], v[98:101], v[174:177], v[20:23]
	global_load_lds_dwordx4 v192, s[14:15]
	v_mfma_f32_16x16x32_f16 v[4:7], v[102:105], v[174:177], v[4:7]
	s_waitcnt lgkmcnt(2)
	s_add_u32 m0, s12, 0x4000
	v_mfma_f32_16x16x32_f16 v[48:51], v[90:93], v[178:181], v[48:51]
	global_load_lds_dwordx4 v190, s[8:9]
	v_mfma_f32_16x16x32_f16 v[32:35], v[94:97], v[178:181], v[32:35]
	s_add_u32 m0, s12, 0x5000
	v_mfma_f32_16x16x32_f16 v[16:19], v[98:101], v[178:181], v[16:19]
	global_load_lds_dwordx4 v191, s[8:9]
	v_mfma_f32_16x16x32_f16 v[0:3], v[102:105], v[178:181], v[0:3]
	s_waitcnt lgkmcnt(1)
	s_add_u32 m0, s12, 0x6000
	v_mfma_f32_16x16x32_f16 v[52:55], v[106:109], v[182:185], v[52:55]
	global_load_lds_dwordx4 v192, s[8:9]
	v_mfma_f32_16x16x32_f16 v[36:39], v[110:113], v[182:185], v[36:39]
	v_mfma_f32_16x16x32_f16 v[20:23], v[114:117], v[182:185], v[20:23]
	v_mfma_f32_16x16x32_f16 v[4:7], v[118:121], v[182:185], v[4:7]
	s_waitcnt lgkmcnt(0)
	s_add_u32 m0, s12, 0x7000
	v_mfma_f32_16x16x32_f16 v[48:51], v[106:109], v[186:189], v[48:51]
	global_load_lds_dwordx4 v193, s[8:9]
	v_mfma_f32_16x16x32_f16 v[32:35], v[110:113], v[186:189], v[32:35]
	v_mfma_f32_16x16x32_f16 v[16:19], v[114:117], v[186:189], v[16:19]
	v_mfma_f32_16x16x32_f16 v[0:3], v[118:121], v[186:189], v[0:3]
	s_add_u32 s14, s14, 128
	s_addc_u32 s15, s15, 0
	s_add_u32 s8, s8, 128
	s_addc_u32 s9, s9, 0
	s_waitcnt vmcnt(8)
	s_barrier
	ds_read_b128 v[132:135], v196 offset:8192
	ds_read_b128 v[90:93], v194 offset:0
	ds_read_b128 v[94:97], v194 offset:2048
	ds_read_b128 v[98:101], v194 offset:4096
	ds_read_b128 v[102:105], v194 offset:6144
	ds_read_b128 v[136:139], v196 offset:10240
	ds_read_b128 v[106:109], v195 offset:0
	ds_read_b128 v[110:113], v195 offset:2048
	ds_read_b128 v[114:117], v195 offset:4096
	ds_read_b128 v[118:121], v195 offset:6144
	ds_read_b128 v[140:143], v197 offset:8192
	ds_read_b128 v[144:147], v197 offset:10240
	s_waitcnt lgkmcnt(10)
	s_add_u32 m0, s12, 0x8000
	v_mfma_f32_16x16x32_f16 v[124:127], v[90:93], v[132:135], v[124:127]
	global_load_lds_dwordx4 v190, s[10:11]
	s_waitcnt lgkmcnt(9)
	v_mfma_f32_16x16x32_f16 v[44:47], v[94:97], v[132:135], v[44:47]
	s_waitcnt lgkmcnt(8)
	v_mfma_f32_16x16x32_f16 v[28:31], v[98:101], v[132:135], v[28:31]
	s_waitcnt lgkmcnt(7)
	v_mfma_f32_16x16x32_f16 v[12:15], v[102:105], v[132:135], v[12:15]
	s_waitcnt lgkmcnt(6)
	s_add_u32 m0, s12, 0x9000
	v_mfma_f32_16x16x32_f16 v[56:59], v[90:93], v[136:139], v[56:59]
	global_load_lds_dwordx4 v192, s[10:11]
	v_mfma_f32_16x16x32_f16 v[40:43], v[94:97], v[136:139], v[40:43]
	v_mfma_f32_16x16x32_f16 v[24:27], v[98:101], v[136:139], v[24:27]
	v_mfma_f32_16x16x32_f16 v[8:11], v[102:105], v[136:139], v[8:11]
	s_waitcnt lgkmcnt(1)
	v_mfma_f32_16x16x32_f16 v[124:127], v[106:109], v[140:143], v[124:127]
	v_mfma_f32_16x16x32_f16 v[44:47], v[110:113], v[140:143], v[44:47]
	v_mfma_f32_16x16x32_f16 v[28:31], v[114:117], v[140:143], v[28:31]
	v_mfma_f32_16x16x32_f16 v[12:15], v[118:121], v[140:143], v[12:15]
	s_waitcnt lgkmcnt(0)
	v_mfma_f32_16x16x32_f16 v[56:59], v[106:109], v[144:147], v[56:59]
	v_mfma_f32_16x16x32_f16 v[40:43], v[110:113], v[144:147], v[40:43]
	v_mfma_f32_16x16x32_f16 v[24:27], v[114:117], v[144:147], v[24:27]
	v_mfma_f32_16x16x32_f16 v[8:11], v[118:121], v[144:147], v[8:11]
	s_add_u32 s10, s10, 128
	s_addc_u32 s11, s11, 0
	s_barrier
	ds_read_b128 v[174:177], v196 offset:16384
	ds_read_b128 v[178:181], v196 offset:18432
	ds_read_b128 v[182:185], v197 offset:16384
	ds_read_b128 v[186:189], v197 offset:18432
	s_waitcnt lgkmcnt(3)
	s_add_u32 m0, s12, 0xa000
	v_mfma_f32_16x16x32_f16 v[52:55], v[90:93], v[174:177], v[52:55]
	global_load_lds_dwordx4 v190, s[14:15]
	v_mfma_f32_16x16x32_f16 v[36:39], v[94:97], v[174:177], v[36:39]
	s_add_u32 m0, s12, 0xb000
	v_mfma_f32_16x16x32_f16 v[20:23], v[98:101], v[174:177], v[20:23]
	global_load_lds_dwordx4 v192, s[14:15]
	v_mfma_f32_16x16x32_f16 v[4:7], v[102:105], v[174:177], v[4:7]
	s_waitcnt lgkmcnt(2)
	s_add_u32 m0, s12, 0x0
	v_mfma_f32_16x16x32_f16 v[48:51], v[90:93], v[178:181], v[48:51]
	global_load_lds_dwordx4 v190, s[8:9]
	v_mfma_f32_16x16x32_f16 v[32:35], v[94:97], v[178:181], v[32:35]
	s_add_u32 m0, s12, 0x1000
	v_mfma_f32_16x16x32_f16 v[16:19], v[98:101], v[178:181], v[16:19]
	global_load_lds_dwordx4 v191, s[8:9]
	v_mfma_f32_16x16x32_f16 v[0:3], v[102:105], v[178:181], v[0:3]
	s_waitcnt lgkmcnt(1)
	s_add_u32 m0, s12, 0x2000
	v_mfma_f32_16x16x32_f16 v[52:55], v[106:109], v[182:185], v[52:55]
	global_load_lds_dwordx4 v192, s[8:9]
	v_mfma_f32_16x16x32_f16 v[36:39], v[110:113], v[182:185], v[36:39]
	v_mfma_f32_16x16x32_f16 v[20:23], v[114:117], v[182:185], v[20:23]
	v_mfma_f32_16x16x32_f16 v[4:7], v[118:121], v[182:185], v[4:7]
	s_waitcnt lgkmcnt(0)
	s_add_u32 m0, s12, 0x3000
	v_mfma_f32_16x16x32_f16 v[48:51], v[106:109], v[186:189], v[48:51]
	global_load_lds_dwordx4 v193, s[8:9]
	v_mfma_f32_16x16x32_f16 v[32:35], v[110:113], v[186:189], v[32:35]
	v_mfma_f32_16x16x32_f16 v[16:19], v[114:117], v[186:189], v[16:19]
	v_mfma_f32_16x16x32_f16 v[0:3], v[118:121], v[186:189], v[0:3]
	s_add_u32 s14, s14, 128
	s_addc_u32 s15, s15, 0
	s_add_u32 s8, s8, 128
	s_addc_u32 s9, s9, 0
	s_waitcnt vmcnt(8)
	s_barrier
	ds_read_b128 v[132:135], v196 offset:24576
	ds_read_b128 v[90:93], v194 offset:16384
	ds_read_b128 v[94:97], v194 offset:18432
	ds_read_b128 v[98:101], v194 offset:20480
	ds_read_b128 v[102:105], v194 offset:22528
	ds_read_b128 v[136:139], v196 offset:26624
	ds_read_b128 v[106:109], v195 offset:16384
	ds_read_b128 v[110:113], v195 offset:18432
	ds_read_b128 v[114:117], v195 offset:20480
	ds_read_b128 v[118:121], v195 offset:22528
	ds_read_b128 v[140:143], v197 offset:24576
	ds_read_b128 v[144:147], v197 offset:26624
	s_waitcnt lgkmcnt(10)
	s_add_u32 m0, s12, 0xc000
	v_mfma_f32_16x16x32_f16 v[124:127], v[90:93], v[132:135], v[124:127]
	global_load_lds_dwordx4 v190, s[10:11]
	s_waitcnt lgkmcnt(9)
	v_mfma_f32_16x16x32_f16 v[44:47], v[94:97], v[132:135], v[44:47]
	s_waitcnt lgkmcnt(8)
	v_mfma_f32_16x16x32_f16 v[28:31], v[98:101], v[132:135], v[28:31]
	s_waitcnt lgkmcnt(7)
	v_mfma_f32_16x16x32_f16 v[12:15], v[102:105], v[132:135], v[12:15]
	s_waitcnt lgkmcnt(6)
	s_add_u32 m0, s12, 0xd000
	v_mfma_f32_16x16x32_f16 v[56:59], v[90:93], v[136:139], v[56:59]
	global_load_lds_dwordx4 v192, s[10:11]
	v_mfma_f32_16x16x32_f16 v[40:43], v[94:97], v[136:139], v[40:43]
	v_mfma_f32_16x16x32_f16 v[24:27], v[98:101], v[136:139], v[24:27]
	v_mfma_f32_16x16x32_f16 v[8:11], v[102:105], v[136:139], v[8:11]
	s_waitcnt lgkmcnt(1)
	v_mfma_f32_16x16x32_f16 v[124:127], v[106:109], v[140:143], v[124:127]
	v_mfma_f32_16x16x32_f16 v[44:47], v[110:113], v[140:143], v[44:47]
	v_mfma_f32_16x16x32_f16 v[28:31], v[114:117], v[140:143], v[28:31]
	v_mfma_f32_16x16x32_f16 v[12:15], v[118:121], v[140:143], v[12:15]
	s_waitcnt lgkmcnt(0)
	v_mfma_f32_16x16x32_f16 v[56:59], v[106:109], v[144:147], v[56:59]
	v_mfma_f32_16x16x32_f16 v[40:43], v[110:113], v[144:147], v[40:43]
	v_mfma_f32_16x16x32_f16 v[24:27], v[114:117], v[144:147], v[24:27]
	v_mfma_f32_16x16x32_f16 v[8:11], v[118:121], v[144:147], v[8:11]
	s_add_u32 s10, s10, 128
	s_addc_u32 s11, s11, 0
	s_barrier
	ds_read_b128 v[174:177], v196 offset:32768
	ds_read_b128 v[178:181], v196 offset:34816
	ds_read_b128 v[182:185], v197 offset:32768
	ds_read_b128 v[186:189], v197 offset:34816
	s_waitcnt lgkmcnt(3)
	s_add_u32 m0, s12, 0xe000
	v_mfma_f32_16x16x32_f16 v[52:55], v[90:93], v[174:177], v[52:55]
	global_load_lds_dwordx4 v190, s[14:15]
	v_mfma_f32_16x16x32_f16 v[36:39], v[94:97], v[174:177], v[36:39]
	s_add_u32 m0, s12, 0xf000
	v_mfma_f32_16x16x32_f16 v[20:23], v[98:101], v[174:177], v[20:23]
	global_load_lds_dwordx4 v192, s[14:15]
	v_mfma_f32_16x16x32_f16 v[4:7], v[102:105], v[174:177], v[4:7]
	s_waitcnt lgkmcnt(2)
	s_add_u32 m0, s12, 0x4000
	v_mfma_f32_16x16x32_f16 v[48:51], v[90:93], v[178:181], v[48:51]
	global_load_lds_dwordx4 v190, s[8:9]
	v_mfma_f32_16x16x32_f16 v[32:35], v[94:97], v[178:181], v[32:35]
	s_add_u32 m0, s12, 0x5000
	v_mfma_f32_16x16x32_f16 v[16:19], v[98:101], v[178:181], v[16:19]
	global_load_lds_dwordx4 v191, s[8:9]
	v_mfma_f32_16x16x32_f16 v[0:3], v[102:105], v[178:181], v[0:3]
	s_waitcnt lgkmcnt(1)
	s_add_u32 m0, s12, 0x6000
	v_mfma_f32_16x16x32_f16 v[52:55], v[106:109], v[182:185], v[52:55]
	global_load_lds_dwordx4 v192, s[8:9]
	v_mfma_f32_16x16x32_f16 v[36:39], v[110:113], v[182:185], v[36:39]
	v_mfma_f32_16x16x32_f16 v[20:23], v[114:117], v[182:185], v[20:23]
	v_mfma_f32_16x16x32_f16 v[4:7], v[118:121], v[182:185], v[4:7]
	s_waitcnt lgkmcnt(0)
	s_add_u32 m0, s12, 0x7000
	v_mfma_f32_16x16x32_f16 v[48:51], v[106:109], v[186:189], v[48:51]
	global_load_lds_dwordx4 v193, s[8:9]
	v_mfma_f32_16x16x32_f16 v[32:35], v[110:113], v[186:189], v[32:35]
	v_mfma_f32_16x16x32_f16 v[16:19], v[114:117], v[186:189], v[16:19]
	v_mfma_f32_16x16x32_f16 v[0:3], v[118:121], v[186:189], v[0:3]
	s_add_u32 s14, s14, 128
	s_addc_u32 s15, s15, 0
	s_add_u32 s8, s8, 128
	s_addc_u32 s9, s9, 0
	s_add_i32 s13, s13, 1
	s_cmp_lt_u32 s13, 3
	s_cbranch_scc1 .Lgout_loop
	global_load_dwordx4 v[60:63], v148, s[38:39] offset:0
	global_load_dwordx4 v[64:67], v148, s[38:39] offset:64
	global_load_dwordx4 v[68:71], v148, s[38:39] offset:128
	global_load_dwordx4 v[72:75], v148, s[38:39] offset:192
	global_load_dwordx4 v[76:79], v150, s[36:37] offset:0
	global_load_dwordx4 v[80:83], v150, s[36:37] offset:64
	global_load_dwordx4 v[84:87], v150, s[36:37] offset:128
	global_load_dwordx4 v[200:203], v150, s[36:37] offset:192
	global_load_dwordx4 v[204:207], v151, s[36:37] offset:0
	global_load_dwordx4 v[210:213], v151, s[36:37] offset:64
	global_load_dwordx4 v[222:225], v151, s[36:37] offset:128
	global_load_dwordx4 v[226:229], v151, s[36:37] offset:192
	global_load_dwordx4 v[230:233], v152, s[36:37] offset:0
	global_load_dwordx4 v[234:237], v152, s[36:37] offset:64
	global_load_dwordx4 v[238:241], v152, s[36:37] offset:128
	global_load_dwordx4 v[242:245], v152, s[36:37] offset:192
	global_load_dwordx4 v[246:249], v153, s[36:37] offset:0
	global_load_dwordx4 v[158:161], v153, s[36:37] offset:64
	global_load_dwordx4 v[162:165], v153, s[36:37] offset:128
	global_load_dwordx4 v[154:157], v153, s[36:37] offset:192
	s_waitcnt vmcnt(28)
	s_barrier
	ds_read_b128 v[132:135], v196 offset:0
	ds_read_b128 v[90:93], v194 offset:0
	ds_read_b128 v[94:97], v194 offset:2048
	ds_read_b128 v[98:101], v194 offset:4096
	ds_read_b128 v[102:105], v194 offset:6144
	ds_read_b128 v[136:139], v196 offset:2048
	ds_read_b128 v[106:109], v195 offset:0
	ds_read_b128 v[110:113], v195 offset:2048
	ds_read_b128 v[114:117], v195 offset:4096
	ds_read_b128 v[118:121], v195 offset:6144
	ds_read_b128 v[140:143], v197 offset:0
	ds_read_b128 v[144:147], v197 offset:2048
	s_waitcnt lgkmcnt(10)
	v_mfma_f32_16x16x32_f16 v[124:127], v[90:93], v[132:135], v[124:127]
	s_waitcnt lgkmcnt(9)
	v_mfma_f32_16x16x32_f16 v[44:47], v[94:97], v[132:135], v[44:47]
	s_waitcnt lgkmcnt(8)
	v_mfma_f32_16x16x32_f16 v[28:31], v[98:101], v[132:135], v[28:31]
	s_waitcnt lgkmcnt(7)
	v_mfma_f32_16x16x32_f16 v[12:15], v[102:105], v[132:135], v[12:15]
	s_waitcnt lgkmcnt(6)
	v_mfma_f32_16x16x32_f16 v[56:59], v[90:93], v[136:139], v[56:59]
	v_mfma_f32_16x16x32_f16 v[40:43], v[94:97], v[136:139], v[40:43]
	v_mfma_f32_16x16x32_f16 v[24:27], v[98:101], v[136:139], v[24:27]
	v_mfma_f32_16x16x32_f16 v[8:11], v[102:105], v[136:139], v[8:11]
	s_waitcnt lgkmcnt(1)
	v_mfma_f32_16x16x32_f16 v[124:127], v[106:109], v[140:143], v[124:127]
	v_mfma_f32_16x16x32_f16 v[44:47], v[110:113], v[140:143], v[44:47]
	v_mfma_f32_16x16x32_f16 v[28:31], v[114:117], v[140:143], v[28:31]
	v_mfma_f32_16x16x32_f16 v[12:15], v[118:121], v[140:143], v[12:15]
	s_waitcnt lgkmcnt(0)
	v_mfma_f32_16x16x32_f16 v[56:59], v[106:109], v[144:147], v[56:59]
	v_mfma_f32_16x16x32_f16 v[40:43], v[110:113], v[144:147], v[40:43]
	v_mfma_f32_16x16x32_f16 v[24:27], v[114:117], v[144:147], v[24:27]
	v_mfma_f32_16x16x32_f16 v[8:11], v[118:121], v[144:147], v[8:11]
	s_barrier
	ds_read_b128 v[174:177], v196 offset:8192
	ds_read_b128 v[178:181], v196 offset:10240
	ds_read_b128 v[182:185], v197 offset:8192
	ds_read_b128 v[186:189], v197 offset:10240
	s_waitcnt lgkmcnt(3)
	v_mfma_f32_16x16x32_f16 v[52:55], v[90:93], v[174:177], v[52:55]
	v_mfma_f32_16x16x32_f16 v[36:39], v[94:97], v[174:177], v[36:39]
	v_mfma_f32_16x16x32_f16 v[20:23], v[98:101], v[174:177], v[20:23]
	v_mfma_f32_16x16x32_f16 v[4:7], v[102:105], v[174:177], v[4:7]
	s_waitcnt lgkmcnt(2)
	v_mfma_f32_16x16x32_f16 v[48:51], v[90:93], v[178:181], v[48:51]
	v_mfma_f32_16x16x32_f16 v[32:35], v[94:97], v[178:181], v[32:35]
	v_mfma_f32_16x16x32_f16 v[16:19], v[98:101], v[178:181], v[16:19]
	v_mfma_f32_16x16x32_f16 v[0:3], v[102:105], v[178:181], v[0:3]
	s_waitcnt lgkmcnt(1)
	v_mfma_f32_16x16x32_f16 v[52:55], v[106:109], v[182:185], v[52:55]
	v_mfma_f32_16x16x32_f16 v[36:39], v[110:113], v[182:185], v[36:39]
	v_mfma_f32_16x16x32_f16 v[20:23], v[114:117], v[182:185], v[20:23]
	v_mfma_f32_16x16x32_f16 v[4:7], v[118:121], v[182:185], v[4:7]
	s_waitcnt lgkmcnt(0)
	v_mfma_f32_16x16x32_f16 v[48:51], v[106:109], v[186:189], v[48:51]
	v_mfma_f32_16x16x32_f16 v[32:35], v[110:113], v[186:189], v[32:35]
	v_mfma_f32_16x16x32_f16 v[16:19], v[114:117], v[186:189], v[16:19]
	v_mfma_f32_16x16x32_f16 v[0:3], v[118:121], v[186:189], v[0:3]
	s_waitcnt vmcnt(20)
	s_barrier
	ds_read_b128 v[132:135], v196 offset:16384
	ds_read_b128 v[90:93], v194 offset:16384
	ds_read_b128 v[94:97], v194 offset:18432
	ds_read_b128 v[98:101], v194 offset:20480
	ds_read_b128 v[102:105], v194 offset:22528
	ds_read_b128 v[136:139], v196 offset:18432
	ds_read_b128 v[106:109], v195 offset:16384
	ds_read_b128 v[110:113], v195 offset:18432
	ds_read_b128 v[114:117], v195 offset:20480
	ds_read_b128 v[118:121], v195 offset:22528
	ds_read_b128 v[140:143], v197 offset:16384
	ds_read_b128 v[144:147], v197 offset:18432
	s_waitcnt lgkmcnt(10)
	v_mfma_f32_16x16x32_f16 v[124:127], v[90:93], v[132:135], v[124:127]
	s_waitcnt lgkmcnt(9)
	v_mfma_f32_16x16x32_f16 v[44:47], v[94:97], v[132:135], v[44:47]
	s_waitcnt lgkmcnt(8)
	v_mfma_f32_16x16x32_f16 v[28:31], v[98:101], v[132:135], v[28:31]
	s_waitcnt lgkmcnt(7)
	v_mfma_f32_16x16x32_f16 v[12:15], v[102:105], v[132:135], v[12:15]
	s_waitcnt lgkmcnt(6)
	v_mfma_f32_16x16x32_f16 v[56:59], v[90:93], v[136:139], v[56:59]
	v_mfma_f32_16x16x32_f16 v[40:43], v[94:97], v[136:139], v[40:43]
	v_mfma_f32_16x16x32_f16 v[24:27], v[98:101], v[136:139], v[24:27]
	v_mfma_f32_16x16x32_f16 v[8:11], v[102:105], v[136:139], v[8:11]
	s_waitcnt lgkmcnt(1)
	v_mfma_f32_16x16x32_f16 v[124:127], v[106:109], v[140:143], v[124:127]
	v_mfma_f32_16x16x32_f16 v[44:47], v[110:113], v[140:143], v[44:47]
	v_mfma_f32_16x16x32_f16 v[28:31], v[114:117], v[140:143], v[28:31]
	v_mfma_f32_16x16x32_f16 v[12:15], v[118:121], v[140:143], v[12:15]
	s_waitcnt lgkmcnt(0)
	v_mfma_f32_16x16x32_f16 v[56:59], v[106:109], v[144:147], v[56:59]
	v_mfma_f32_16x16x32_f16 v[40:43], v[110:113], v[144:147], v[40:43]
	v_mfma_f32_16x16x32_f16 v[24:27], v[114:117], v[144:147], v[24:27]
	v_mfma_f32_16x16x32_f16 v[8:11], v[118:121], v[144:147], v[8:11]
	s_barrier
	ds_read_b128 v[174:177], v196 offset:24576
	ds_read_b128 v[178:181], v196 offset:26624
	ds_read_b128 v[182:185], v197 offset:24576
	ds_read_b128 v[186:189], v197 offset:26624
	s_waitcnt lgkmcnt(3)
	v_mfma_f32_16x16x32_f16 v[52:55], v[90:93], v[174:177], v[52:55]
	v_mfma_f32_16x16x32_f16 v[36:39], v[94:97], v[174:177], v[36:39]
	v_mfma_f32_16x16x32_f16 v[20:23], v[98:101], v[174:177], v[20:23]
	v_mfma_f32_16x16x32_f16 v[4:7], v[102:105], v[174:177], v[4:7]
	s_waitcnt lgkmcnt(2)
	v_mfma_f32_16x16x32_f16 v[48:51], v[90:93], v[178:181], v[48:51]
	v_mfma_f32_16x16x32_f16 v[32:35], v[94:97], v[178:181], v[32:35]
	v_mfma_f32_16x16x32_f16 v[16:19], v[98:101], v[178:181], v[16:19]
	v_mfma_f32_16x16x32_f16 v[0:3], v[102:105], v[178:181], v[0:3]
	s_waitcnt lgkmcnt(1)
	v_mfma_f32_16x16x32_f16 v[52:55], v[106:109], v[182:185], v[52:55]
	v_mfma_f32_16x16x32_f16 v[36:39], v[110:113], v[182:185], v[36:39]
	v_mfma_f32_16x16x32_f16 v[20:23], v[114:117], v[182:185], v[20:23]
	v_mfma_f32_16x16x32_f16 v[4:7], v[118:121], v[182:185], v[4:7]
	s_waitcnt lgkmcnt(0)
	v_mfma_f32_16x16x32_f16 v[48:51], v[106:109], v[186:189], v[48:51]
	v_mfma_f32_16x16x32_f16 v[32:35], v[110:113], v[186:189], v[32:35]
	v_mfma_f32_16x16x32_f16 v[16:19], v[114:117], v[186:189], v[16:19]
	v_mfma_f32_16x16x32_f16 v[0:3], v[118:121], v[186:189], v[0:3]
	s_nop 7
	s_waitcnt vmcnt(0)
	v_pk_mul_f32 v[124:125], v[124:125], v[60:61]
	v_pk_mul_f32 v[126:127], v[126:127], v[62:63]
	v_pk_fma_f32 v[124:125], v[76:77], s[96:97], v[124:125] op_sel_hi:[1,0,1]
	v_pk_fma_f32 v[126:127], v[78:79], s[96:97], v[126:127] op_sel_hi:[1,0,1]
	global_store_dwordx4 v150, v[124:127], s[18:19] offset:0
	v_pk_mul_f32 v[44:45], v[44:45], v[64:65]
	v_pk_mul_f32 v[46:47], v[46:47], v[66:67]
	v_pk_fma_f32 v[44:45], v[80:81], s[96:97], v[44:45] op_sel_hi:[1,0,1]
	v_pk_fma_f32 v[46:47], v[82:83], s[96:97], v[46:47] op_sel_hi:[1,0,1]
	global_store_dwordx4 v150, v[44:47], s[18:19] offset:64
	v_pk_mul_f32 v[28:29], v[28:29], v[68:69]
	v_pk_mul_f32 v[30:31], v[30:31], v[70:71]
	v_pk_fma_f32 v[28:29], v[84:85], s[96:97], v[28:29] op_sel_hi:[1,0,1]
	v_pk_fma_f32 v[30:31], v[86:87], s[96:97], v[30:31] op_sel_hi:[1,0,1]
	global_store_dwordx4 v150, v[28:31], s[18:19] offset:128
	v_pk_mul_f32 v[12:13], v[12:13], v[72:73]
	v_pk_mul_f32 v[14:15], v[14:15], v[74:75]
	v_pk_fma_f32 v[12:13], v[200:201], s[96:97], v[12:13] op_sel_hi:[1,0,1]
	v_pk_fma_f32 v[14:15], v[202:203], s[96:97], v[14:15] op_sel_hi:[1,0,1]
	global_store_dwordx4 v150, v[12:15], s[18:19] offset:192
	v_pk_mul_f32 v[56:57], v[56:57], v[60:61]
	v_pk_mul_f32 v[58:59], v[58:59], v[62:63]
	v_pk_fma_f32 v[56:57], v[204:205], s[96:97], v[56:57] op_sel_hi:[1,0,1]
	v_pk_fma_f32 v[58:59], v[206:207], s[96:97], v[58:59] op_sel_hi:[1,0,1]
	global_store_dwordx4 v151, v[56:59], s[18:19] offset:0
	v_pk_mul_f32 v[40:41], v[40:41], v[64:65]
	v_pk_mul_f32 v[42:43], v[42:43], v[66:67]
	v_pk_fma_f32 v[40:41], v[210:211], s[96:97], v[40:41] op_sel_hi:[1,0,1]
	v_pk_fma_f32 v[42:43], v[212:213], s[96:97], v[42:43] op_sel_hi:[1,0,1]
	global_store_dwordx4 v151, v[40:43], s[18:19] offset:64
	v_pk_mul_f32 v[24:25], v[24:25], v[68:69]
	v_pk_mul_f32 v[26:27], v[26:27], v[70:71]
	v_pk_fma_f32 v[24:25], v[222:223], s[96:97], v[24:25] op_sel_hi:[1,0,1]
	v_pk_fma_f32 v[26:27], v[224:225], s[96:97], v[26:27] op_sel_hi:[1,0,1]
	global_store_dwordx4 v151, v[24:27], s[18:19] offset:128
	v_pk_mul_f32 v[8:9], v[8:9], v[72:73]
	v_pk_mul_f32 v[10:11], v[10:11], v[74:75]
	v_pk_fma_f32 v[8:9], v[226:227], s[96:97], v[8:9] op_sel_hi:[1,0,1]
	v_pk_fma_f32 v[10:11], v[228:229], s[96:97], v[10:11] op_sel_hi:[1,0,1]
	global_store_dwordx4 v151, v[8:11], s[18:19] offset:192
	v_pk_mul_f32 v[52:53], v[52:53], v[60:61]
	v_pk_mul_f32 v[54:55], v[54:55], v[62:63]
	v_pk_fma_f32 v[52:53], v[230:231], s[96:97], v[52:53] op_sel_hi:[1,0,1]
	v_pk_fma_f32 v[54:55], v[232:233], s[96:97], v[54:55] op_sel_hi:[1,0,1]
	global_store_dwordx4 v152, v[52:55], s[18:19] offset:0
	v_pk_mul_f32 v[36:37], v[36:37], v[64:65]
	v_pk_mul_f32 v[38:39], v[38:39], v[66:67]
	v_pk_fma_f32 v[36:37], v[234:235], s[96:97], v[36:37] op_sel_hi:[1,0,1]
	v_pk_fma_f32 v[38:39], v[236:237], s[96:97], v[38:39] op_sel_hi:[1,0,1]
	global_store_dwordx4 v152, v[36:39], s[18:19] offset:64
	v_pk_mul_f32 v[20:21], v[20:21], v[68:69]
	v_pk_mul_f32 v[22:23], v[22:23], v[70:71]
	v_pk_fma_f32 v[20:21], v[238:239], s[96:97], v[20:21] op_sel_hi:[1,0,1]
	v_pk_fma_f32 v[22:23], v[240:241], s[96:97], v[22:23] op_sel_hi:[1,0,1]
	global_store_dwordx4 v152, v[20:23], s[18:19] offset:128
	v_pk_mul_f32 v[4:5], v[4:5], v[72:73]
	v_pk_mul_f32 v[6:7], v[6:7], v[74:75]
	v_pk_fma_f32 v[4:5], v[242:243], s[96:97], v[4:5] op_sel_hi:[1,0,1]
	v_pk_fma_f32 v[6:7], v[244:245], s[96:97], v[6:7] op_sel_hi:[1,0,1]
	global_store_dwordx4 v152, v[4:7], s[18:19] offset:192
	v_pk_mul_f32 v[48:49], v[48:49], v[60:61]
	v_pk_mul_f32 v[50:51], v[50:51], v[62:63]
	v_pk_fma_f32 v[48:49], v[246:247], s[96:97], v[48:49] op_sel_hi:[1,0,1]
	v_pk_fma_f32 v[50:51], v[248:249], s[96:97], v[50:51] op_sel_hi:[1,0,1]
	global_store_dwordx4 v153, v[48:51], s[18:19] offset:0
	v_pk_mul_f32 v[32:33], v[32:33], v[64:65]
	v_pk_mul_f32 v[34:35], v[34:35], v[66:67]
	v_pk_fma_f32 v[32:33], v[158:159], s[96:97], v[32:33] op_sel_hi:[1,0,1]
	v_pk_fma_f32 v[34:35], v[160:161], s[96:97], v[34:35] op_sel_hi:[1,0,1]
	global_store_dwordx4 v153, v[32:35], s[18:19] offset:64
	v_pk_mul_f32 v[16:17], v[16:17], v[68:69]
	v_pk_mul_f32 v[18:19], v[18:19], v[70:71]
	v_pk_fma_f32 v[16:17], v[162:163], s[96:97], v[16:17] op_sel_hi:[1,0,1]
	v_pk_fma_f32 v[18:19], v[164:165], s[96:97], v[18:19] op_sel_hi:[1,0,1]
	global_store_dwordx4 v153, v[16:19], s[18:19] offset:128
	v_pk_mul_f32 v[0:1], v[0:1], v[72:73]
	v_pk_mul_f32 v[2:3], v[2:3], v[74:75]
	v_pk_fma_f32 v[0:1], v[154:155], s[96:97], v[0:1] op_sel_hi:[1,0,1]
	v_pk_fma_f32 v[2:3], v[156:157], s[96:97], v[2:3] op_sel_hi:[1,0,1]
	global_store_dwordx4 v153, v[0:3], s[18:19] offset:192
	s_add_i32 s6, s6, 1
	s_lshl_b32 s0, s6, 3
	v_readlane_b32 s4, v254, 36
	s_or_b32 s0, s0, s4
	v_readlane_b32 s4, v254, 37
	s_mul_i32 s0, s0, s4
	v_readlane_b32 s4, v254, 38
	s_add_i32 s0, s0, s4
	s_cmpk_gt_u32 s0, 0x5ff
	s_cbranch_scc1 .LBB0_1481
	s_branch .LBB0_1352
